# per-phase pointer-table loads issued before the grid barrier wait instead of after it
# baseline (speedup 1.0000x reference)
; __device__ __forceinline__ unsigned xb_ld(unsigned* p)              { return __hip_atomic_load(p, __ATOMIC_RELAXED, __HIP_MEMORY_SCOPE_AGENT); }
; __device__ __forceinline__ void xcd_barrier_complete(unsigned* bar, unsigned x, unsigned& nloc, unsigned& nx) {
;     const unsigned G = gridDim.x * gridDim.y * gridDim.z;
;     unsigned sum, cnt, mine, sp = 0u;
;     for (;;) {
;         sum = 0u; cnt = 0u; mine = 0u;
; #pragma unroll
;         for (unsigned j = 0; j < 16; ++j) { const unsigned c = xb_ld(&bar[XB_XCNT(j)]); sum += c; cnt += (c > 0u) ? 1u : 0u; mine = (j == x) ? c : mine; }
;         if (sum == G) break;
;         __builtin_amdgcn_s_sleep(1);
;         if ((++sp & 255u) == 0u) { if (xb_ld(&bar[XB_TMO])) break; if (sp > XB_SPIN_CAP) { atomicAdd(&bar[XB_TMO], 1u); break; } }
;     }
;     nloc = mine > 0u ? mine : 1u; nx = cnt > 0u ? cnt : 1u;
; }
; __global__ void __launch_bounds__(NTHREADS, 2) fwd_megakernel(Params p) {
;     ...
;     const XcdBarrier xbar = xcd_barrier_post((unsigned*)(p.ws + WS_BAR), xst);
;     int ph = p.ph_lo;
.LBB0_295:
	s_load_dwordx2 s[20:21], s[0:1], 0xb0
	s_lshl_b32 s4, s80, 9
	v_writelane_b32 v252, s4, 5
	s_mov_b32 s15, 0
	s_mov_b32 s31, s6
	s_waitcnt lgkmcnt(0)
	s_lshl_b32 s4, s20, 3
	s_and_b32 s4, s4, 0x3fffff8
	s_cmpk_gt_i32 s80, 0xff
	v_writelane_b32 v252, s4, 6
	s_cselect_b64 s[4:5], -1, 0
	v_writelane_b32 v252, s4, 7
	s_cmpk_lt_u32 s80, 0x1b0
	s_mov_b32 s86, 0xfff58000
	v_writelane_b32 v252, s5, 8
	s_cselect_b64 s[4:5], -1, 0
	v_writelane_b32 v252, s4, 9
	s_ashr_i32 s7, s20, 31
	s_lshl_b32 s30, s20, 9
	v_writelane_b32 v252, s5, 10
	s_and_b32 s4, s80, 7
	v_writelane_b32 v252, s4, 11
	s_bfe_u32 s4, s80, 0x50003
	v_writelane_b32 v252, s4, 12
	s_lshl_b32 s14, s4, 9
	v_writelane_b32 v252, s14, 13
	s_ashr_i32 s4, s80, 31
	s_mov_b32 s88, 0xfffe0000
	v_writelane_b32 v252, s15, 14
	v_writelane_b32 v252, s4, 15
	s_lshr_b32 s4, s4, 29
	s_add_i32 s5, s80, s4
	s_ashr_i32 s4, s5, 3
	s_and_b32 s5, s5, -8
	s_sub_i32 s5, s80, s5
	s_lshl_b32 s6, s5, 5
	s_cmpk_lt_i32 s80, 0x5ac
	v_writelane_b32 v252, s7, 16
	s_cselect_b64 s[8:9], -1, 0
	v_writelane_b32 v252, s8, 17
	s_mul_i32 s7, s5, 0xb5
	s_add_i32 s7, s7, 4
	v_writelane_b32 v252, s9, 18
	s_add_i32 s8, s80, 0x84d
	v_writelane_b32 v252, s8, 19
	s_and_b32 s8, s80, 0x7fffff80
	s_cmpk_eq_i32 s8, 0x100
	s_cselect_b64 s[8:9], -1, 0
	v_writelane_b32 v252, s8, 20
	v_mov_b32_e32 v211, 0x419c8000
	v_mov_b32_e32 v212, 0x358637bd
	v_writelane_b32 v252, s9, 21
	s_bfe_u32 s8, s80, 0x40003
	s_lshl_b32 s14, s8, 8
	v_writelane_b32 v252, s8, 22
	s_add_u32 s8, s26, 0x419c8800
	s_addc_u32 s9, s27, 0
	s_add_u32 s22, s26, 0x419c8a00
	v_writelane_b32 v252, s8, 23
	s_addc_u32 s23, s27, 0
	v_mov_b32_e32 v213, 1
	v_writelane_b32 v252, s9, 24
	s_add_u32 s8, s26, 0x419c8b00
	s_addc_u32 s9, s27, 0
	v_writelane_b32 v252, s8, 25
	v_mov_b32_e32 v214, 0x3ecc95a3
	v_mov_b64_e32 v[216:217], 0xff
	v_writelane_b32 v252, s9, 26
	s_add_u32 s8, s26, 0x419c8c00
	s_addc_u32 s9, s27, 0
	v_writelane_b32 v252, s8, 27
	v_mov_b32_e32 v218, 0xc50
	v_mov_b32_e32 v219, 0xff800000
	v_writelane_b32 v252, s9, 28
	s_add_u32 s8, s26, 0x419c8d00
	s_addc_u32 s9, s27, 0
	v_writelane_b32 v252, s8, 29
	v_mov_b32_e32 v220, 0x60
	v_mov_b32_e32 v221, 0x7f800000
	v_writelane_b32 v252, s9, 30
	s_add_u32 s8, s26, 0x419c8e00
	s_addc_u32 s9, s27, 0
	v_writelane_b32 v252, s8, 31
	v_mov_b32_e32 v222, 0x7fc00000
	s_movk_i32 s81, 0x2a00
	v_writelane_b32 v252, s9, 32
	s_add_u32 s8, s26, 0x419c8f00
	s_addc_u32 s9, s27, 0
	v_writelane_b32 v252, s8, 33
	s_mov_b64 s[82:83], 0x40000
	s_mov_b64 s[84:85], 0x20000
	v_writelane_b32 v252, s9, 34
	s_add_u32 s8, s26, 0x419c9000
	s_addc_u32 s9, s27, 0
	v_writelane_b32 v252, s8, 35
	s_mov_b32 s87, -1
	s_mov_b32 s89, -1
	v_writelane_b32 v252, s9, 36
	s_add_u32 s8, s26, 0x419c9100
	s_addc_u32 s9, s27, 0
	v_writelane_b32 v252, s8, 37
	s_nop 1
	v_writelane_b32 v252, s9, 38
	s_add_u32 s8, s26, 0x419c9200
	s_addc_u32 s9, s27, 0
	v_writelane_b32 v252, s8, 39
	s_nop 1
	v_writelane_b32 v252, s9, 40
	s_add_u32 s8, s26, 0x419c9300
	s_addc_u32 s9, s27, 0
	v_writelane_b32 v252, s8, 41
	s_nop 1
	v_writelane_b32 v252, s9, 42
	s_add_u32 s8, s26, 0x419c9400
	s_addc_u32 s9, s27, 0
	v_writelane_b32 v252, s8, 43
	s_nop 1
	v_writelane_b32 v252, s9, 44
	s_add_u32 s8, s26, 0x419c9500
	s_addc_u32 s9, s27, 0
	v_writelane_b32 v252, s8, 45
	s_nop 1
	v_writelane_b32 v252, s9, 46
	s_add_u32 s8, s26, 0x419c9600
	s_addc_u32 s9, s27, 0
	v_writelane_b32 v252, s8, 47
	s_nop 1
	v_writelane_b32 v252, s9, 48
	s_add_u32 s8, s26, 0x419c9700
	s_addc_u32 s9, s27, 0
	v_writelane_b32 v252, s8, 49
	s_nop 1
	v_writelane_b32 v252, s9, 50
	s_add_u32 s8, s26, 0x419c9800
	s_addc_u32 s9, s27, 0
	v_writelane_b32 v252, s8, 51
	s_nop 1
	v_writelane_b32 v252, s9, 52
	s_add_u32 s8, s26, 0x419c9900
	s_addc_u32 s9, s27, 0
	v_writelane_b32 v252, s8, 53
	s_cmp_eq_u32 s3, 15
	s_nop 0
	v_writelane_b32 v252, s9, 54
	s_cselect_b64 s[8:9], -1, 0
	v_writelane_b32 v252, s8, 55
	s_cmp_eq_u32 s3, 14
	s_nop 0
	v_writelane_b32 v252, s9, 56
	s_cselect_b64 s[8:9], -1, 0
	v_writelane_b32 v252, s8, 57
	s_cmp_eq_u32 s3, 13
	s_nop 0
	v_writelane_b32 v252, s9, 58
	s_cselect_b64 s[8:9], -1, 0
	v_writelane_b32 v252, s8, 59
	s_cmp_eq_u32 s3, 12
	s_nop 0
	v_writelane_b32 v252, s9, 60
	s_cselect_b64 s[8:9], -1, 0
	v_writelane_b32 v252, s8, 61
	s_cmp_eq_u32 s3, 11
	s_nop 0
	v_writelane_b32 v252, s9, 62
	s_cselect_b64 s[8:9], -1, 0
	v_writelane_b32 v252, s8, 63
	s_cmp_eq_u32 s3, 10
	s_nop 0
	v_writelane_b32 v253, s9, 0
	s_cselect_b64 s[8:9], -1, 0
	v_writelane_b32 v253, s8, 1
	s_cmp_eq_u32 s3, 9
	s_nop 0
	v_writelane_b32 v253, s9, 2
	s_cselect_b64 s[8:9], -1, 0
	v_writelane_b32 v253, s8, 3
	s_cmp_eq_u32 s3, 8
	s_nop 0
	v_writelane_b32 v253, s9, 4
	s_cselect_b64 s[8:9], -1, 0
	v_writelane_b32 v253, s8, 5
	s_cmp_eq_u32 s3, 7
	s_nop 0
	v_writelane_b32 v253, s9, 6
	s_cselect_b64 s[8:9], -1, 0
	v_writelane_b32 v253, s8, 7
	s_cmp_eq_u32 s3, 6
	s_nop 0
	v_writelane_b32 v253, s9, 8
	s_cselect_b64 s[8:9], -1, 0
	v_writelane_b32 v253, s8, 9
	s_cmp_eq_u32 s3, 5
	s_nop 0
	v_writelane_b32 v253, s9, 10
	s_cselect_b64 s[8:9], -1, 0
	v_writelane_b32 v253, s8, 11
	s_cmp_eq_u32 s3, 4
	s_nop 0
	v_writelane_b32 v253, s9, 12
	s_cselect_b64 s[8:9], -1, 0
	v_writelane_b32 v253, s8, 13
	s_cmp_eq_u32 s3, 3
	s_nop 0
	v_writelane_b32 v253, s9, 14
	s_cselect_b64 s[8:9], -1, 0
	v_writelane_b32 v253, s8, 15
	s_cmp_eq_u32 s3, 2
	s_nop 0
	v_writelane_b32 v253, s9, 16
	s_cselect_b64 s[8:9], -1, 0
	v_writelane_b32 v253, s8, 17
	s_cmp_eq_u32 s3, 1
	s_nop 0
	v_writelane_b32 v253, s9, 18
	s_cselect_b64 s[8:9], -1, 0
	v_writelane_b32 v253, s8, 19
	s_cmp_eq_u32 s3, 0
	s_nop 0
	v_writelane_b32 v253, s9, 20
	s_cselect_b64 s[8:9], -1, 0
	s_lshl_b32 s3, s3, 8
; #define LAS __attribute__((address_space(3)))
;     __device__ bool next(int i, Unit& u) const {
;         const long L = (long)i * G + c; if (L >= nwg) return false;
;         int wgid = (int)L; { const int q = nwg / NXCD, r = nwg % NXCD, xcd = wgid % NXCD, off = wgid / NXCD; wgid = (xcd < r ? xcd * (q + 1) : r * (q + 1) + (xcd - r) * q) + off; }
;         const int nig = WGM * nN, gid = wgid / nig, fm = gid * WGM, gsz = (nM - fm) < WGM ? (nM - fm) : WGM;
;         u.pm = fm + ((wgid % nig) % gsz); u.pn = (wgid % nig) / gsz; u.k0t = 0; u.nt = ntk; u.part = -1; return true;
;     }
; __device__ __forceinline__ void convert_gap(const Params& p, int layer, int nwg, int base, int per, LAS unsigned char* lds) {
;     if (layer + 1 >= NLAYER) return;
;     const int G = gridDim.x, c = blockIdx.x, rem = nwg % G;
;     const int limit = base == GAP_PRE ? GAP_BASE6 : CT_LAYER;
;     if (rem == 0) { __syncthreads(); convert_jobs<false>(p, (layer + 1) * CT_LAYER + base + c, (layer + 1) * CT_LAYER + limit, G, lds); return; }
;     if (c < rem) return;
;     const int slot = c - rem, nslots = G - rem;
;     int j0 = base + slot * per, j1 = j0 + per;
;     if (slot == nslots - 1 || j1 > limit) j1 = limit;
;     if (j0 > limit) j0 = limit;
	v_writelane_b32 v253, s8, 21
	s_add_u32 s3, s28, s3
	s_nop 0
	v_writelane_b32 v253, s9, 22
	s_addc_u32 s8, s29, 0
	s_add_u32 s10, s3, 0x1400
	s_addc_u32 s11, s8, 0
	v_writelane_b32 v253, s10, 23
	s_nop 1
	v_writelane_b32 v253, s11, 24
	s_add_u32 s10, s3, 0x2400
	s_addc_u32 s11, s8, 0
	v_writelane_b32 v253, s10, 25
	s_add_u32 s8, s26, 0x419cba00
	s_addc_u32 s9, s27, 0
	v_writelane_b32 v253, s11, 26
	v_writelane_b32 v253, s8, 27
	s_mul_i32 s3, s5, 57
	s_nop 0
	v_writelane_b32 v253, s9, 28
	s_add_u32 s8, s26, 0x419cbb00
	s_addc_u32 s9, s27, 0
	v_writelane_b32 v253, s8, 29
	s_cmpk_lt_i32 s80, 0x1ce
	s_mov_b64 s[26:27], 0x80
	v_writelane_b32 v253, s9, 30
	s_cselect_b64 s[8:9], -1, 0
	v_writelane_b32 v253, s8, 31
	s_nop 1
	v_writelane_b32 v253, s9, 32
	s_add_i32 s8, s3, 6
	s_add_i32 s3, s20, -8
	s_cmp_ge_i32 s80, s3
	s_cselect_b64 s[10:11], -1, 0
	s_not_b32 s3, s80
	s_add_i32 s3, s20, s3
	v_writelane_b32 v253, s10, 33
	s_cmpk_lt_i32 s80, 0x2b5
	s_mul_i32 s9, s5, 0x56
	v_writelane_b32 v253, s11, 34
	s_cselect_b64 s[10:11], -1, 0
	v_writelane_b32 v253, s10, 35
	s_add_i32 s9, s9, 5
	s_nop 0
	v_writelane_b32 v253, s11, 36
	s_add_i32 s10, s80, 0x514
	v_writelane_b32 v253, s10, 37
	s_cmp_lt_i32 s5, 0
	s_mul_i32 s10, s5, 33
	s_cselect_b32 s6, s10, s6
	s_add_i32 s6, s6, s4
	s_ashr_i32 s10, s6, 31
	s_lshr_b32 s10, s10, 26
	s_add_i32 s10, s6, s10
	s_and_b32 s11, s10, 0xffc0
	s_sub_i32 s6, s6, s11
	s_bfe_i32 s11, s6, 0x80000
	s_bfe_u32 s11, s11, 0x3000c
	s_add_i32 s11, s6, s11
	s_and_b32 s12, s11, 0xf8
	s_sub_i32 s6, s6, s12
	s_ashr_i32 s10, s10, 6
	s_lshl_b32 s10, s10, 3
	s_sext_i32_i8 s6, s6
	s_add_i32 s6, s6, s10
	s_bfe_i32 s10, s11, 0x80000
	s_sext_i32_i16 s10, s10
	s_ashr_i32 s10, s10, 3
	v_writelane_b32 v253, s10, 38
	s_add_i32 s6, s6, 1
	v_writelane_b32 v253, s6, 39
	s_cmp_lt_i32 s5, 4
	s_mul_i32 s6, s5, 0xb6
	s_cselect_b32 s6, s6, s7
	s_add_i32 s6, s6, s4
	s_mul_hi_i32 s7, s6, 0x2e8ba2e9
	s_lshr_b32 s10, s7, 31
	s_ashr_i32 s7, s7, 6
	s_add_i32 s7, s7, s10
	s_mul_i32 s10, s7, 0x160
	s_lshl_b32 s7, s7, 3
	s_sub_i32 s10, s6, s10
	s_sub_i32 s6, 33, s7
	s_min_u32 s11, s6, 8
	s_cmp_lt_i32 s5, 6
	s_mul_i32 s6, s5, 58
	s_cselect_b32 s6, s6, s8
	s_add_i32 s6, s6, s4
	s_mul_hi_i32 s8, s6, 0x92492493
	s_add_i32 s8, s8, s6
	s_lshr_b32 s12, s8, 31
	s_ashr_i32 s8, s8, 6
	s_add_i32 s8, s8, s12
	s_mul_i32 s12, s8, 0x70
	s_lshl_b32 s8, s8, 3
	s_sub_i32 s12, s6, s12
	s_sub_i32 s6, 33, s8
	s_min_u32 s13, s6, 8
	s_cmp_lt_i32 s5, 5
	s_mulk_i32 s5, 0x57
	s_cselect_b32 s5, s5, s9
	v_cvt_f32_ubyte0_e32 v1, s11
	s_add_i32 s5, s5, s4
	v_cvt_f32_i32_e32 v0, s10
	v_rcp_iflag_f32_e32 v2, v1
	s_mul_hi_i32 s4, s5, 0x30c30c31
	s_lshr_b32 s6, s4, 31
	s_ashr_i32 s4, s4, 5
	s_add_i32 s4, s4, s6
	s_lshl_b32 s16, s4, 3
	v_mul_f32_e32 v2, v0, v2
	s_mul_i32 s6, s4, 0xa8
	s_sub_i32 s4, 33, s16
	v_trunc_f32_e32 v2, v2
	s_min_u32 s17, s4, 8
	s_ashr_i32 s4, s10, 30
	v_fma_f32 v0, -v2, v1, v0
	s_sub_i32 s9, s5, s6
	s_or_b32 s6, s4, 1
	v_cmp_ge_f32_e64 s[4:5], |v0|, v1
	v_cvt_i32_f32_e32 v0, v2
	s_and_b64 s[4:5], s[4:5], exec
	s_cselect_b32 s4, s6, 0
	v_cvt_f32_ubyte0_e32 v1, s13
	v_readfirstlane_b32 s5, v0
	s_add_i32 s6, s5, s4
	s_mul_i32 s4, s6, s11
	s_sub_i32 s4, s10, s4
	s_abs_i32 s10, s20
	v_cvt_f32_u32_e32 v0, s10
	s_sub_i32 s5, 0, s10
	s_sext_i32_i16 s4, s4
	s_add_i32 s24, s7, s4
	v_rcp_iflag_f32_e32 v0, v0
	s_mov_b32 s18, s24
	s_ashr_i32 s25, s24, 31
	v_rcp_iflag_f32_e32 v2, v1
	v_mul_f32_e32 v0, 0x4f7ffffe, v0
	v_cvt_u32_f32_e32 v0, v0
	s_nop 0
	v_readfirstlane_b32 s11, v0
	s_mul_i32 s5, s5, s11
	s_mul_hi_u32 s5, s11, s5
	s_add_i32 s11, s11, s5
	s_bfe_i64 s[4:5], s[6:7], 0x100000
	s_lshl_b64 s[4:5], s[4:5], 20
	v_writelane_b32 v253, s4, 40
	v_cvt_f32_i32_e32 v0, s12
	v_mul_f32_e32 v2, v0, v2
	v_writelane_b32 v253, s5, 41
	s_mul_hi_u32 s4, s11, 0x5ac
	s_mul_i32 s4, s4, s10
	s_sub_i32 s4, 0x5ac, s4
	v_writelane_b32 v253, s18, 42
	s_sub_i32 s5, s4, s10
	v_trunc_f32_e32 v2, v2
	v_writelane_b32 v253, s19, 43
	s_lshl_b64 s[18:19], s[24:25], 20
	s_cmp_ge_u32 s4, s10
	s_cselect_b32 s4, s5, s4
	s_sub_i32 s5, s4, s10
	s_cmp_ge_u32 s4, s10
	s_cselect_b32 s4, s5, s4
	v_writelane_b32 v253, s18, 44
	s_cmp_lg_u32 s4, 0
	v_fma_f32 v0, -v2, v1, v0
	v_writelane_b32 v253, s19, 45
	s_cselect_b64 s[18:19], -1, 0
	v_writelane_b32 v253, s18, 46
	s_cmp_ge_i32 s80, s4
	s_nop 0
	v_writelane_b32 v253, s19, 47
	s_cselect_b64 s[18:19], -1, 0
	s_sub_i32 s5, s80, s4
; #define LAS __attribute__((address_space(3)))
; __device__ __forceinline__ void convert_gap(const Params& p, int layer, int nwg, int base, int per, LAS unsigned char* lds) {
;     if (layer + 1 >= NLAYER) return;
;     const int G = gridDim.x, c = blockIdx.x, rem = nwg % G;
;     const int limit = base == GAP_PRE ? GAP_BASE6 : CT_LAYER;
;     if (rem == 0) { __syncthreads(); convert_jobs<false>(p, (layer + 1) * CT_LAYER + base + c, (layer + 1) * CT_LAYER + limit, G, lds); return; }
;     if (c < rem) return;
;     const int slot = c - rem, nslots = G - rem;
;     int j0 = base + slot * per, j1 = j0 + per;
;     if (slot == nslots - 1 || j1 > limit) j1 = limit;
;     if (j0 > limit) j0 = limit;
;     __syncthreads();
;     convert_jobs<false>(p, (layer + 1) * CT_LAYER + j0, (layer + 1) * CT_LAYER + j1, 1, lds);
; }
; __device__ __forceinline__ void run_phase(const Params& pin, int ph, LAS unsigned char* lds, const XcdBarrier& xb) {
;     ...
;     {
;         const float* const* tab = (const float* const*)(p.ws + WS_PTRS);
; #pragma unroll
;         for (int i = 0; i < 19; ++i) { const unsigned long long v = (unsigned long long)tab[i];
;             const unsigned lo = __builtin_amdgcn_readfirstlane((unsigned)v), hi2 = __builtin_amdgcn_readfirstlane((unsigned)(v >> 32));
;             p.in[i] = (const float*)(const __attribute__((address_space(1))) float*)(((unsigned long long)hi2 << 32) | lo); }
;     }
	v_writelane_b32 v253, s18, 48
	s_mul_i32 s7, s5, 13
	s_not_b32 s4, s4
	v_writelane_b32 v253, s19, 49
	s_min_u32 s18, s7, 0x3f6
	s_add_i32 s4, s20, s4
	s_addk_i32 s18, 0x85a
	s_cmp_lg_u32 s5, s4
	s_cselect_b32 s5, s18, 0xc50
	s_min_u32 s4, s7, 0x403
	s_addk_i32 s4, 0x84d
	v_writelane_b32 v253, s5, 50
	s_cmp_lt_u32 s4, s5
	v_writelane_b32 v253, s4, 51
	s_cselect_b64 s[4:5], -1, 0
	v_writelane_b32 v253, s4, 52
	s_nop 1
	v_writelane_b32 v253, s5, 53
	s_ashr_i32 s4, s12, 30
	s_or_b32 s7, s4, 1
	v_cmp_ge_f32_e64 s[4:5], |v0|, v1
	v_cvt_i32_f32_e32 v0, v2
	s_and_b64 s[4:5], s[4:5], exec
	v_cvt_f32_ubyte0_e32 v1, s17
	s_cselect_b32 s4, s7, 0
	v_readfirstlane_b32 s5, v0
	v_cvt_f32_i32_e32 v0, s9
	v_rcp_iflag_f32_e32 v2, v1
	s_add_i32 s7, s5, s4
	s_mul_i32 s4, s7, s13
	s_sub_i32 s4, s12, s4
	s_sext_i32_i8 s4, s4
	v_mul_f32_e32 v2, v0, v2
	s_add_i32 s4, s8, s4
	v_trunc_f32_e32 v2, v2
	v_writelane_b32 v253, s4, 54
	s_ashr_i32 s4, s9, 30
	v_fma_f32 v0, -v2, v1, v0
	s_or_b32 s8, s4, 1
	v_cmp_ge_f32_e64 s[4:5], |v0|, v1
	v_cvt_i32_f32_e32 v0, v2
	s_and_b64 s[4:5], s[4:5], exec
	s_cselect_b32 s4, s8, 0
	v_mov_b32_e32 v1, 0
	v_readfirstlane_b32 s5, v0
	s_add_i32 s8, s5, s4
	s_mul_i32 s4, s8, s17
	s_sub_i32 s4, s9, s4
	s_sext_i32_i16 s4, s4
	s_add_i32 s4, s16, s4
	v_writelane_b32 v253, s4, 55
	s_mul_hi_u32 s4, s11, 0x2b5
	s_mul_i32 s4, s4, s10
	s_sub_i32 s4, 0x2b5, s4
	s_sub_i32 s5, s4, s10
	s_cmp_ge_u32 s4, s10
	s_cselect_b32 s4, s5, s4
	s_sub_i32 s5, s4, s10
	s_cmp_ge_u32 s4, s10
	s_cselect_b32 s4, s5, s4
	s_cmp_lg_u32 s4, 0
	s_cselect_b64 s[10:11], -1, 0
	v_writelane_b32 v253, s10, 56
	s_cmp_ge_i32 s80, s4
	v_mbcnt_lo_u32_b32 v0, -1, 0
	v_writelane_b32 v253, s11, 57
	s_cselect_b64 s[10:11], -1, 0
	s_sub_i32 s5, s80, s4
	v_writelane_b32 v253, s10, 58
	s_mul_i32 s9, s5, 11
	s_not_b32 s4, s4
	v_writelane_b32 v253, s11, 59
	s_min_u32 s10, s9, 0x32e
	s_add_i32 s4, s20, s4
	s_addk_i32 s10, 0x51f
	s_cmp_lg_u32 s5, s4
	s_mul_i32 s4, s21, s20
	s_mul_i32 s47, s4, s2
	s_sext_i32_i16 s2, s6
	v_writelane_b32 v253, s2, 60
	s_sext_i32_i8 s2, s7
	v_writelane_b32 v253, s2, 61
	s_sext_i32_i16 s2, s8
	s_mul_hi_i32 s5, s3, 0x2100
	s_mul_i32 s4, s3, 0x2100
	v_writelane_b32 v253, s2, 62
	s_cselect_b32 s3, s10, 0x84d
	s_min_u32 s2, s9, 0x339
	s_addk_i32 s2, 0x514
	v_writelane_b32 v254, s2, 0
	s_cmp_lt_u32 s2, s3
	v_writelane_b32 v254, s14, 1
	v_writelane_b32 v253, s3, 63
	s_cselect_b64 s[2:3], -1, 0
	v_writelane_b32 v254, s15, 2
	v_writelane_b32 v254, s2, 3
	s_and_b32 s14, s20, 0x7fffff
	s_lshl_b32 s25, s20, 12
	v_writelane_b32 v254, s3, 4
	s_lshl_b32 s2, s14, 4
	s_addk_i32 s2, 0xff
	v_writelane_b32 v254, s2, 5
	s_lshl_b64 s[2:3], s[4:5], 2
	v_writelane_b32 v254, s2, 6
	s_load_dwordx4 s[4:7], s[0:1], 0x98
	s_lshl_b64 s[0:1], s[14:15], 15
	v_writelane_b32 v254, s3, 7
	s_lshl_b32 s2, s80, 12
	v_writelane_b32 v254, s2, 8
	s_mul_i32 s2, s14, 0x15000
	v_writelane_b32 v254, s2, 9
	s_add_i32 s2, 0, 0x1fff0
	v_writelane_b32 v254, s2, 10
	s_add_i32 s2, 0, 0x10100
	v_writelane_b32 v254, s2, 11
	s_add_i32 s2, 0, 0x20004
	v_writelane_b32 v254, s2, 12
	s_waitcnt lgkmcnt(0)
	v_writelane_b32 v254, s4, 13
	v_mbcnt_hi_u32_b32 v215, -1, v0
	s_nop 0
	v_writelane_b32 v254, s5, 14
	v_writelane_b32 v254, s6, 15
	v_writelane_b32 v254, s7, 16
	v_writelane_b32 v254, s0, 17
	s_nop 1
	v_writelane_b32 v254, s1, 18
	s_lshl_b64 s[0:1], s[14:15], 16
	v_writelane_b32 v254, s0, 19
	s_nop 1
	v_writelane_b32 v254, s1, 20
	s_lshl_b64 s[0:1], s[14:15], 14
	v_writelane_b32 v254, s0, 21
	s_nop 1
	v_writelane_b32 v254, s1, 22
	v_writelane_b32 v254, s30, 23
	v_writelane_b32 v254, s47, 24
	v_writelane_b32 v254, s25, 25
	v_writelane_b32 v254, s22, 26
	s_nop 1
	v_writelane_b32 v254, s23, 27
	v_readlane_b32 s100, v254, 15
	v_readlane_b32 s101, v254, 16
	s_nop 1
	s_add_u32 s100, s100, 0x419c8500
	s_addc_u32 s101, s101, 0
	global_load_dwordx4 v[160:163], v1, s[100:101]
	global_load_dwordx4 v[164:167], v1, s[100:101] offset:16
	global_load_dwordx4 v[168:171], v1, s[100:101] offset:32
	global_load_dwordx4 v[172:175], v1, s[100:101] offset:48
	global_load_dwordx4 v[176:179], v1, s[100:101] offset:64
	global_load_dwordx4 v[180:183], v1, s[100:101] offset:80
	global_load_dwordx4 v[184:187], v1, s[100:101] offset:96
	global_load_dwordx4 v[188:191], v1, s[100:101] offset:112
	global_load_dwordx4 v[192:195], v1, s[100:101] offset:128
	global_load_dwordx2 v[196:197], v1, s[100:101] offset:144
	s_branch .LBB0_299

; #define LAS __attribute__((address_space(3)))
; __device__ __forceinline__ void run_phase(const Params& pin, int ph, LAS unsigned char* lds, const XcdBarrier& xb) {
;     Params p; p.ws = pin.ws; p.out = pin.out; p.ph_lo = pin.ph_lo; p.ph_hi = pin.ph_hi; asm volatile("" : "+s"(p.ws));
;     { unsigned long long uw = (unsigned long long)p.ws, uo = (unsigned long long)p.out; asm volatile("" : "+s"(uw), "+s"(uo));
;       p.ws = (unsigned char*)(__attribute__((address_space(1))) unsigned char*)uw;
;       p.out = (float*)(__attribute__((address_space(1))) float*)uo; }
;     {
;         const float* const* tab = (const float* const*)(p.ws + WS_PTRS);
; #pragma unroll
;         for (int i = 0; i < 19; ++i) { const unsigned long long v = (unsigned long long)tab[i];
;             const unsigned lo = __builtin_amdgcn_readfirstlane((unsigned)v), hi2 = __builtin_amdgcn_readfirstlane((unsigned)(v >> 32));
;             p.in[i] = (const float*)(const __attribute__((address_space(1))) float*)(((unsigned long long)hi2 << 32) | lo); }
;     }
;     const int layer = (ph - 1) / 9, s = (ph - 1) % 9;
.LBB0_299:
	v_readlane_b32 s0, v254, 13
	v_readlane_b32 s2, v254, 15
	v_readlane_b32 s3, v254, 16
	s_mov_b64 s[34:35], s[2:3]
	v_readlane_b32 s1, v254, 14
	s_nop 0
	s_add_u32 s2, s34, 0x419c8500
	s_addc_u32 s3, s35, 0
	s_waitcnt lgkmcnt(0)
	s_add_u32 s2, s34, 0x419c8540
	s_addc_u32 s3, s35, 0
	s_add_u32 s2, s34, 0x419c8580
	s_addc_u32 s3, s35, 0
	s_add_i32 s2, s31, -1
	s_mul_hi_i32 s3, s2, 0x38e38e39
	s_lshr_b32 s4, s3, 31
	s_ashr_i32 s3, s3, 1
	s_add_i32 s90, s3, s4
	s_mul_i32 s3, s90, 9
	s_sub_i32 s50, s2, s3
	s_cmp_lt_i32 s50, 0
	s_waitcnt vmcnt(0)
	v_readfirstlane_b32 s11, v165
	v_readfirstlane_b32 s39, v161
	v_readfirstlane_b32 s38, v160
	v_readfirstlane_b32 s41, v163
	v_readfirstlane_b32 s40, v162
	v_readfirstlane_b32 s9, v177
	v_readfirstlane_b32 s10, v176
	v_readfirstlane_b32 s4, v179
	v_readfirstlane_b32 s5, v178
	v_readfirstlane_b32 s12, v164
	v_readfirstlane_b32 s16, v167
	v_readfirstlane_b32 s17, v166
	s_waitcnt vmcnt(6)
	v_readfirstlane_b32 s48, v169
	v_readfirstlane_b32 s49, v168
	v_readfirstlane_b32 s18, v171
	v_readfirstlane_b32 s19, v170
	s_waitcnt vmcnt(5)
	v_readfirstlane_b32 s20, v173
	v_readfirstlane_b32 s21, v172
	v_readfirstlane_b32 s23, v175
	v_readfirstlane_b32 s22, v174
	s_waitcnt vmcnt(4)
	v_readfirstlane_b32 s2, v193
	v_readfirstlane_b32 s14, v192
	v_readfirstlane_b32 s29, v195
	v_readfirstlane_b32 s33, v194
	s_waitcnt vmcnt(3)
	v_readfirstlane_b32 s7, v181
	v_readfirstlane_b32 s8, v180
	v_readfirstlane_b32 s36, v183
	v_readfirstlane_b32 s37, v182
	s_waitcnt vmcnt(2)
	v_readfirstlane_b32 s13, v185
	v_readfirstlane_b32 s46, v184
	v_readfirstlane_b32 s42, v187
	v_readfirstlane_b32 s43, v186
	s_waitcnt vmcnt(1)
	v_readfirstlane_b32 s44, v189
	v_readfirstlane_b32 s45, v188
	v_readfirstlane_b32 s24, v191
	v_readfirstlane_b32 s28, v190
	s_waitcnt vmcnt(0)
	v_readfirstlane_b32 s3, v197
	v_readfirstlane_b32 s6, v196
	s_cbranch_scc0 .LBB0_300
	s_getpc_b64 s[98:99]

; __device__ __forceinline__ void xcd_barrier(const XcdBarrier& b) {
;     asm volatile("s_waitcnt vmcnt(0)" ::: "memory");
;     __syncthreads();
;     if (threadIdx.x == 0) {
;         unsigned* bar = b.bar;
;         __builtin_amdgcn_s_waitcnt(0);
;         unsigned nloc = b.st[0], nx = b.st[1];
;         if (nloc == 0u) { xcd_barrier_complete(bar, b.x, nloc, nx); b.st[0] = nloc; b.st[1] = nx; }
; __device__ __forceinline__ void run_phase(const Params& pin, int ph, LAS unsigned char* lds, const XcdBarrier& xb) {
;     ...
;     {
;         const float* const* tab = (const float* const*)(p.ws + WS_PTRS);
; #pragma unroll
;         for (int i = 0; i < 19; ++i) { const unsigned long long v = (unsigned long long)tab[i];
;             const unsigned lo = __builtin_amdgcn_readfirstlane((unsigned)v), hi2 = __builtin_amdgcn_readfirstlane((unsigned)(v >> 32));
;             p.in[i] = (const float*)(const __attribute__((address_space(1))) float*)(((unsigned long long)hi2 << 32) | lo); }
.LBB0_1568:
	s_waitcnt vmcnt(0)
	s_waitcnt vmcnt(0) lgkmcnt(0)
	s_barrier
	v_readlane_b32 s100, v254, 15
	v_readlane_b32 s101, v254, 16
	s_nop 1
	s_add_u32 s100, s100, 0x419c8500
	s_addc_u32 s101, s101, 0
	global_load_dwordx4 v[160:163], v1, s[100:101]
	global_load_dwordx4 v[164:167], v1, s[100:101] offset:16
	global_load_dwordx4 v[168:171], v1, s[100:101] offset:32
	global_load_dwordx4 v[172:175], v1, s[100:101] offset:48
	global_load_dwordx4 v[176:179], v1, s[100:101] offset:64
	global_load_dwordx4 v[180:183], v1, s[100:101] offset:80
	global_load_dwordx4 v[184:187], v1, s[100:101] offset:96
	global_load_dwordx4 v[188:191], v1, s[100:101] offset:112
	global_load_dwordx4 v[192:195], v1, s[100:101] offset:128
	global_load_dwordx2 v[196:197], v1, s[100:101] offset:144
	s_mov_b64 s[0:1], exec
	v_readlane_b32 s2, v252, 2
	v_readlane_b32 s3, v252, 3
	s_and_b64 s[2:3], s[0:1], s[2:3]
	s_mov_b64 exec, s[2:3]
	s_cbranch_execnz .LBB0_1569
	s_getpc_b64 s[98:99]
